# K-loops P2/P5/P7: per-segment s_setprio flips removed, static priority 1 for waves 4-7
# speedup vs baseline: 1.0099x; 1.0099x over previous
.LBB0_211:
	s_lshl_b32 s28, s72, 8
	s_ashr_i32 s29, s28, 31
	s_lshl_b64 s[28:29], s[28:29], 11
	s_add_u32 s28, s94, s28
	s_addc_u32 s29, s95, s29
	s_and_b64 s[30:31], s[4:5], exec
	s_cselect_b32 s40, s29, s1
	s_cselect_b32 s41, s28, s0
	s_ashr_i32 s27, s26, 31
	s_lshl_b64 s[30:31], s[26:27], 19
	s_add_u32 s30, s10, s30
	s_addc_u32 s31, s11, s31
	s_and_b64 s[38:39], s[4:5], exec
	s_cselect_b32 s27, s31, s37
	s_cselect_b32 s42, s30, s36
	s_add_u32 s0, s0, 0x40080
	s_addc_u32 s1, s1, 0
	s_add_u32 s43, s36, 0x100
	v_mov_b32_e32 v0, 0
	s_addc_u32 s44, s37, 0
	s_mov_b32 s45, -2
	v_mov_b32_e32 v1, v0
	v_mov_b32_e32 v2, v0
	v_mov_b32_e32 v3, v0
	v_mov_b32_e32 v4, v0
	v_mov_b32_e32 v5, v0
	v_mov_b32_e32 v6, v0
	v_mov_b32_e32 v7, v0
	v_mov_b32_e32 v8, v0
	v_mov_b32_e32 v9, v0
	v_mov_b32_e32 v10, v0
	v_mov_b32_e32 v11, v0
	v_mov_b32_e32 v20, v0
	v_mov_b32_e32 v21, v0
	v_mov_b32_e32 v22, v0
	v_mov_b32_e32 v23, v0
	v_mov_b32_e32 v24, v0
	v_mov_b32_e32 v25, v0
	v_mov_b32_e32 v26, v0
	v_mov_b32_e32 v27, v0
	v_mov_b32_e32 v36, v0
	v_mov_b32_e32 v37, v0
	v_mov_b32_e32 v38, v0
	v_mov_b32_e32 v39, v0
	v_mov_b32_e32 v40, v0
	v_mov_b32_e32 v41, v0
	v_mov_b32_e32 v42, v0
	v_mov_b32_e32 v43, v0
	v_mov_b32_e32 v52, v0
	v_mov_b32_e32 v53, v0
	v_mov_b32_e32 v54, v0
	v_mov_b32_e32 v55, v0
	v_mov_b32_e32 v12, v0
	v_mov_b32_e32 v13, v0
	v_mov_b32_e32 v14, v0
	v_mov_b32_e32 v15, v0
	v_mov_b32_e32 v16, v0
	v_mov_b32_e32 v17, v0
	v_mov_b32_e32 v18, v0
	v_mov_b32_e32 v19, v0
	v_mov_b32_e32 v28, v0
	v_mov_b32_e32 v29, v0
	v_mov_b32_e32 v30, v0
	v_mov_b32_e32 v31, v0
	v_mov_b32_e32 v32, v0
	v_mov_b32_e32 v33, v0
	v_mov_b32_e32 v34, v0
	v_mov_b32_e32 v35, v0
	v_mov_b32_e32 v44, v0
	v_mov_b32_e32 v45, v0
	v_mov_b32_e32 v46, v0
	v_mov_b32_e32 v47, v0
	v_mov_b32_e32 v48, v0
	v_mov_b32_e32 v49, v0
	v_mov_b32_e32 v50, v0
	v_mov_b32_e32 v51, v0
	v_mov_b32_e32 v56, v0
	v_mov_b32_e32 v57, v0
	v_mov_b32_e32 v58, v0
	v_mov_b32_e32 v59, v0
	v_mov_b32_e32 v60, v0
	v_mov_b32_e32 v61, v0
	v_mov_b32_e32 v62, v0
	v_mov_b32_e32 v63, v0
	v_mov_b32_e32 v64, v0
	v_mov_b32_e32 v65, v0
	v_mov_b32_e32 v66, v0
	v_mov_b32_e32 v67, v0
	v_mov_b32_e32 v68, v0
	v_mov_b32_e32 v69, v0
	v_mov_b32_e32 v70, v0
	v_mov_b32_e32 v71, v0
	v_mov_b32_e32 v76, v0
	v_mov_b32_e32 v77, v0
	v_mov_b32_e32 v78, v0
	v_mov_b32_e32 v79, v0
	v_mov_b32_e32 v84, v0
	v_mov_b32_e32 v85, v0
	v_mov_b32_e32 v86, v0
	v_mov_b32_e32 v87, v0
	v_mov_b32_e32 v92, v0
	v_mov_b32_e32 v93, v0
	v_mov_b32_e32 v94, v0
	v_mov_b32_e32 v95, v0
	v_mov_b32_e32 v100, v0
	v_mov_b32_e32 v101, v0
	v_mov_b32_e32 v102, v0
	v_mov_b32_e32 v103, v0
	v_mov_b32_e32 v108, v0
	v_mov_b32_e32 v109, v0
	v_mov_b32_e32 v110, v0
	v_mov_b32_e32 v111, v0
	v_mov_b32_e32 v116, v0
	v_mov_b32_e32 v117, v0
	v_mov_b32_e32 v118, v0
	v_mov_b32_e32 v119, v0
	v_mov_b32_e32 v72, v0
	v_mov_b32_e32 v73, v0
	v_mov_b32_e32 v74, v0
	v_mov_b32_e32 v75, v0
	v_mov_b32_e32 v80, v0
	v_mov_b32_e32 v81, v0
	v_mov_b32_e32 v82, v0
	v_mov_b32_e32 v83, v0
	v_mov_b32_e32 v88, v0
	v_mov_b32_e32 v89, v0
	v_mov_b32_e32 v90, v0
	v_mov_b32_e32 v91, v0
	v_mov_b32_e32 v96, v0
	v_mov_b32_e32 v97, v0
	v_mov_b32_e32 v98, v0
	v_mov_b32_e32 v99, v0
	v_mov_b32_e32 v104, v0
	v_mov_b32_e32 v105, v0
	v_mov_b32_e32 v106, v0
	v_mov_b32_e32 v107, v0
	v_mov_b32_e32 v112, v0
	v_mov_b32_e32 v113, v0
	v_mov_b32_e32 v114, v0
	v_mov_b32_e32 v115, v0
	v_mov_b32_e32 v120, v0
	v_mov_b32_e32 v121, v0
	v_mov_b32_e32 v122, v0
	v_mov_b32_e32 v123, v0
	v_mov_b32_e32 v124, v0
	v_mov_b32_e32 v125, v0
	v_mov_b32_e32 v126, v0
	v_mov_b32_e32 v127, v0
	s_setprio 0
	s_cmp_lt_u32 s3, 0x1000
	s_cbranch_scc1 .Lsprio_p2
	s_setprio 1
.Lsprio_p2:
.LBB0_212:
	ds_read_b128 v[128:131], v175
	ds_read_b128 v[132:135], v175 offset:1024
	ds_read_b128 v[136:139], v175 offset:2048
	ds_read_b128 v[140:143], v175 offset:3072
	ds_read_b128 v[166:169], v176
	ds_read_b128 v[182:185], v176 offset:1024
	ds_read_b128 v[186:189], v176 offset:2048
	ds_read_b128 v[190:193], v176 offset:3072
	s_add_u32 s36, s0, 0xfffc0080
	s_addc_u32 s37, s1, -1
	s_cmp_eq_u32 s45, 12
	s_cselect_b32 s39, s40, s37
	s_cselect_b32 s38, s41, s36
	s_cselect_b32 s37, s27, s44
	s_cselect_b32 s36, s42, s43
	v_lshl_add_u64 v[170:171], s[0:1], 0, v[156:157]
	s_add_i32 m0, s35, 0xc000
	ds_read_b128 v[194:197], v177
	ds_read_b128 v[198:201], v177 offset:1024
	ds_read_b128 v[202:205], v177 offset:2048
	ds_read_b128 v[210:213], v177 offset:3072
	ds_read_b128 v[214:217], v177 offset:4096
	ds_read_b128 v[218:221], v177 offset:5120
	ds_read_b128 v[222:225], v177 offset:6144
	ds_read_b128 v[226:229], v177 offset:7168
	global_load_lds_dwordx4 v[170:171], off
	v_lshl_add_u64 v[170:171], s[0:1], 0, v[158:159]
	s_add_i32 m0, s35, 0xe000
	s_nop 0
	global_load_lds_dwordx4 v[170:171], off
	s_waitcnt vmcnt(8)
	s_waitcnt lgkmcnt(0)
	s_barrier
	s_waitcnt lgkmcnt(0)
	v_mfma_f32_16x16x32_bf16 v[124:127], v[128:131], v[194:197], v[124:127]
	v_mfma_f32_16x16x32_bf16 v[120:123], v[136:139], v[194:197], v[120:123]
	v_mfma_f32_16x16x32_bf16 v[112:115], v[128:131], v[202:205], v[112:115]
	v_mfma_f32_16x16x32_bf16 v[104:107], v[136:139], v[202:205], v[104:107]
	v_mfma_f32_16x16x32_bf16 v[96:99], v[128:131], v[214:217], v[96:99]
	v_mfma_f32_16x16x32_bf16 v[88:91], v[136:139], v[214:217], v[88:91]
	v_mfma_f32_16x16x32_bf16 v[80:83], v[128:131], v[222:225], v[80:83]
	v_mfma_f32_16x16x32_bf16 v[72:75], v[136:139], v[222:225], v[72:75]
	v_mfma_f32_16x16x32_bf16 v[124:127], v[132:135], v[198:201], v[124:127]
	v_mfma_f32_16x16x32_bf16 v[120:123], v[140:143], v[198:201], v[120:123]
	v_mfma_f32_16x16x32_bf16 v[112:115], v[132:135], v[210:213], v[112:115]
	v_mfma_f32_16x16x32_bf16 v[104:107], v[140:143], v[210:213], v[104:107]
	v_mfma_f32_16x16x32_bf16 v[96:99], v[132:135], v[218:221], v[96:99]
	v_mfma_f32_16x16x32_bf16 v[88:91], v[140:143], v[218:221], v[88:91]
	v_mfma_f32_16x16x32_bf16 v[80:83], v[132:135], v[226:229], v[80:83]
	v_mfma_f32_16x16x32_bf16 v[72:75], v[140:143], v[226:229], v[72:75]
	v_mfma_f32_16x16x32_bf16 v[116:119], v[166:169], v[194:197], v[116:119]
	v_mfma_f32_16x16x32_bf16 v[108:111], v[186:189], v[194:197], v[108:111]
	v_mfma_f32_16x16x32_bf16 v[100:103], v[166:169], v[202:205], v[100:103]
	v_mfma_f32_16x16x32_bf16 v[92:95], v[186:189], v[202:205], v[92:95]
	v_mfma_f32_16x16x32_bf16 v[84:87], v[166:169], v[214:217], v[84:87]
	v_mfma_f32_16x16x32_bf16 v[76:79], v[186:189], v[214:217], v[76:79]
	v_mfma_f32_16x16x32_bf16 v[68:71], v[166:169], v[222:225], v[68:71]
	v_mfma_f32_16x16x32_bf16 v[64:67], v[186:189], v[222:225], v[64:67]
	v_mfma_f32_16x16x32_bf16 v[116:119], v[182:185], v[198:201], v[116:119]
	v_mfma_f32_16x16x32_bf16 v[108:111], v[190:193], v[198:201], v[108:111]
	v_mfma_f32_16x16x32_bf16 v[100:103], v[182:185], v[210:213], v[100:103]
	v_mfma_f32_16x16x32_bf16 v[92:95], v[190:193], v[210:213], v[92:95]
	v_mfma_f32_16x16x32_bf16 v[84:87], v[182:185], v[218:221], v[84:87]
	v_mfma_f32_16x16x32_bf16 v[76:79], v[190:193], v[218:221], v[76:79]
	v_mfma_f32_16x16x32_bf16 v[68:71], v[182:185], v[226:229], v[68:71]
	v_mfma_f32_16x16x32_bf16 v[64:67], v[190:193], v[226:229], v[64:67]
	s_barrier
	s_add_i32 s73, s64, s3
	v_lshl_add_u64 v[170:171], s[36:37], 0, v[146:147]
	s_mov_b32 m0, s73
	ds_read_b128 v[194:197], v177 offset:16384
	ds_read_b128 v[198:201], v177 offset:17408
	ds_read_b128 v[202:205], v177 offset:18432
	ds_read_b128 v[210:213], v177 offset:19456
	ds_read_b128 v[214:217], v177 offset:20480
	ds_read_b128 v[218:221], v177 offset:21504
	ds_read_b128 v[222:225], v177 offset:22528
	ds_read_b128 v[226:229], v177 offset:23552
	global_load_lds_dwordx4 v[170:171], off
	s_add_i32 m0, s73, 0x2000
	s_add_u32 s74, s36, 0x40000
	v_lshl_add_u64 v[206:207], s[36:37], 0, v[150:151]
	s_addc_u32 s75, s37, 0
	s_add_i32 s73, s65, s3
	global_load_lds_dwordx4 v[206:207], off
	v_lshl_add_u64 v[230:231], s[74:75], 0, v[146:147]
	s_mov_b32 m0, s73
	v_lshl_add_u64 v[232:233], s[38:39], 0, v[148:149]
	global_load_lds_dwordx4 v[230:231], off
	v_lshl_add_u64 v[230:231], s[74:75], 0, v[150:151]
	s_add_i32 m0, s73, 0x2000
	s_nop 0
	global_load_lds_dwordx4 v[230:231], off
	v_lshl_add_u64 v[230:231], s[38:39], 0, v[144:145]
	s_mov_b32 m0, s35
	s_nop 0
	global_load_lds_dwordx4 v[230:231], off
	s_mov_b32 m0, s46
	s_nop 0
	global_load_lds_dwordx4 v[232:233], off
	s_waitcnt vmcnt(8)
	s_waitcnt lgkmcnt(0)
	s_barrier
	s_waitcnt lgkmcnt(0)
	v_mfma_f32_16x16x32_bf16 v[60:63], v[128:131], v[194:197], v[60:63]
	v_mfma_f32_16x16x32_bf16 v[56:59], v[136:139], v[194:197], v[56:59]
	v_mfma_f32_16x16x32_bf16 v[48:51], v[128:131], v[202:205], v[48:51]
	v_mfma_f32_16x16x32_bf16 v[44:47], v[136:139], v[202:205], v[44:47]
	v_mfma_f32_16x16x32_bf16 v[32:35], v[128:131], v[214:217], v[32:35]
	v_mfma_f32_16x16x32_bf16 v[28:31], v[136:139], v[214:217], v[28:31]
	v_mfma_f32_16x16x32_bf16 v[16:19], v[128:131], v[222:225], v[16:19]
	v_mfma_f32_16x16x32_bf16 v[12:15], v[136:139], v[222:225], v[12:15]
	v_mfma_f32_16x16x32_bf16 v[60:63], v[132:135], v[198:201], v[60:63]
	v_mfma_f32_16x16x32_bf16 v[56:59], v[140:143], v[198:201], v[56:59]
	v_mfma_f32_16x16x32_bf16 v[48:51], v[132:135], v[210:213], v[48:51]
	v_mfma_f32_16x16x32_bf16 v[44:47], v[140:143], v[210:213], v[44:47]
	v_mfma_f32_16x16x32_bf16 v[32:35], v[132:135], v[218:221], v[32:35]
	v_mfma_f32_16x16x32_bf16 v[28:31], v[140:143], v[218:221], v[28:31]
	v_mfma_f32_16x16x32_bf16 v[16:19], v[132:135], v[226:229], v[16:19]
	v_mfma_f32_16x16x32_bf16 v[12:15], v[140:143], v[226:229], v[12:15]
	v_mfma_f32_16x16x32_bf16 v[52:55], v[166:169], v[194:197], v[52:55]
	v_mfma_f32_16x16x32_bf16 v[40:43], v[186:189], v[194:197], v[40:43]
	v_mfma_f32_16x16x32_bf16 v[36:39], v[166:169], v[202:205], v[36:39]
	v_mfma_f32_16x16x32_bf16 v[24:27], v[186:189], v[202:205], v[24:27]
	v_mfma_f32_16x16x32_bf16 v[20:23], v[166:169], v[214:217], v[20:23]
	v_mfma_f32_16x16x32_bf16 v[8:11], v[186:189], v[214:217], v[8:11]
	v_mfma_f32_16x16x32_bf16 v[4:7], v[166:169], v[222:225], v[4:7]
	v_mfma_f32_16x16x32_bf16 v[0:3], v[186:189], v[222:225], v[0:3]
	v_mfma_f32_16x16x32_bf16 v[52:55], v[182:185], v[198:201], v[52:55]
	v_mfma_f32_16x16x32_bf16 v[40:43], v[190:193], v[198:201], v[40:43]
	v_mfma_f32_16x16x32_bf16 v[36:39], v[182:185], v[210:213], v[36:39]
	v_mfma_f32_16x16x32_bf16 v[24:27], v[190:193], v[210:213], v[24:27]
	v_mfma_f32_16x16x32_bf16 v[20:23], v[182:185], v[218:221], v[20:23]
	v_mfma_f32_16x16x32_bf16 v[8:11], v[190:193], v[218:221], v[8:11]
	v_mfma_f32_16x16x32_bf16 v[4:7], v[182:185], v[226:229], v[4:7]
	v_mfma_f32_16x16x32_bf16 v[0:3], v[190:193], v[226:229], v[0:3]
	s_barrier
	s_add_i32 s73, 0, 0x18000
	s_add_i32 s74, 0, 0x1c000
	v_add_u32_e32 v140, s73, v173
	v_add_u32_e32 v152, s74, v173
	ds_read_b128 v[128:131], v140
	ds_read_b128 v[132:135], v140 offset:1024
	ds_read_b128 v[136:139], v140 offset:2048
	ds_read_b128 v[140:143], v140 offset:3072
	ds_read_b128 v[166:169], v152
	ds_read_b128 v[182:185], v152 offset:1024
	ds_read_b128 v[186:189], v152 offset:2048
	ds_read_b128 v[190:193], v152 offset:3072
	s_add_u32 s38, s38, 0x40000
	s_addc_u32 s39, s39, 0
	s_mov_b32 m0, s47
	v_lshl_add_u64 v[234:235], s[38:39], 0, v[144:145]
	ds_read_b128 v[194:197], v177 offset:32768
	ds_read_b128 v[198:201], v177 offset:33792
	ds_read_b128 v[202:205], v177 offset:34816
	ds_read_b128 v[210:213], v177 offset:35840
	ds_read_b128 v[214:217], v177 offset:36864
	ds_read_b128 v[218:221], v177 offset:37888
	ds_read_b128 v[222:225], v177 offset:38912
	ds_read_b128 v[226:229], v177 offset:39936
	global_load_lds_dwordx4 v[234:235], off
	v_lshl_add_u64 v[234:235], s[38:39], 0, v[148:149]
	s_mov_b32 m0, s48
	s_nop 0
	global_load_lds_dwordx4 v[234:235], off
	s_waitcnt vmcnt(8)
	s_waitcnt lgkmcnt(0)
	s_barrier
	s_waitcnt lgkmcnt(0)
	v_mfma_f32_16x16x32_bf16 v[124:127], v[128:131], v[194:197], v[124:127]
	v_mfma_f32_16x16x32_bf16 v[120:123], v[136:139], v[194:197], v[120:123]
	v_mfma_f32_16x16x32_bf16 v[112:115], v[128:131], v[202:205], v[112:115]
	v_mfma_f32_16x16x32_bf16 v[104:107], v[136:139], v[202:205], v[104:107]
	v_mfma_f32_16x16x32_bf16 v[96:99], v[128:131], v[214:217], v[96:99]
	v_mfma_f32_16x16x32_bf16 v[88:91], v[136:139], v[214:217], v[88:91]
	v_mfma_f32_16x16x32_bf16 v[80:83], v[128:131], v[222:225], v[80:83]
	v_mfma_f32_16x16x32_bf16 v[72:75], v[136:139], v[222:225], v[72:75]
	v_mfma_f32_16x16x32_bf16 v[124:127], v[132:135], v[198:201], v[124:127]
	v_mfma_f32_16x16x32_bf16 v[120:123], v[140:143], v[198:201], v[120:123]
	v_mfma_f32_16x16x32_bf16 v[112:115], v[132:135], v[210:213], v[112:115]
	v_mfma_f32_16x16x32_bf16 v[104:107], v[140:143], v[210:213], v[104:107]
	v_mfma_f32_16x16x32_bf16 v[96:99], v[132:135], v[218:221], v[96:99]
	v_mfma_f32_16x16x32_bf16 v[88:91], v[140:143], v[218:221], v[88:91]
	v_mfma_f32_16x16x32_bf16 v[80:83], v[132:135], v[226:229], v[80:83]
	v_mfma_f32_16x16x32_bf16 v[72:75], v[140:143], v[226:229], v[72:75]
	v_mfma_f32_16x16x32_bf16 v[116:119], v[166:169], v[194:197], v[116:119]
	v_mfma_f32_16x16x32_bf16 v[108:111], v[186:189], v[194:197], v[108:111]
	v_mfma_f32_16x16x32_bf16 v[100:103], v[166:169], v[202:205], v[100:103]
	v_mfma_f32_16x16x32_bf16 v[92:95], v[186:189], v[202:205], v[92:95]
	v_mfma_f32_16x16x32_bf16 v[84:87], v[166:169], v[214:217], v[84:87]
	v_mfma_f32_16x16x32_bf16 v[76:79], v[186:189], v[214:217], v[76:79]
	v_mfma_f32_16x16x32_bf16 v[68:71], v[166:169], v[222:225], v[68:71]
	v_mfma_f32_16x16x32_bf16 v[64:67], v[186:189], v[222:225], v[64:67]
	v_mfma_f32_16x16x32_bf16 v[116:119], v[182:185], v[198:201], v[116:119]
	v_mfma_f32_16x16x32_bf16 v[108:111], v[190:193], v[198:201], v[108:111]
	v_mfma_f32_16x16x32_bf16 v[100:103], v[182:185], v[210:213], v[100:103]
	v_mfma_f32_16x16x32_bf16 v[92:95], v[190:193], v[210:213], v[92:95]
	v_mfma_f32_16x16x32_bf16 v[84:87], v[182:185], v[218:221], v[84:87]
	v_mfma_f32_16x16x32_bf16 v[76:79], v[190:193], v[218:221], v[76:79]
	v_mfma_f32_16x16x32_bf16 v[68:71], v[182:185], v[226:229], v[68:71]
	v_mfma_f32_16x16x32_bf16 v[64:67], v[190:193], v[226:229], v[64:67]
	s_barrier
	s_add_i32 s38, s73, s3
	v_lshl_add_u64 v[170:171], v[170:171], 0, s[18:19]
	s_mov_b32 m0, s38
	ds_read_b128 v[194:197], v177 offset:49152
	ds_read_b128 v[198:201], v177 offset:50176
	ds_read_b128 v[202:205], v177 offset:51200
	ds_read_b128 v[210:213], v177 offset:52224
	ds_read_b128 v[214:217], v177 offset:53248
	ds_read_b128 v[218:221], v177 offset:54272
	ds_read_b128 v[222:225], v177 offset:55296
	ds_read_b128 v[226:229], v177 offset:56320
	global_load_lds_dwordx4 v[170:171], off
	s_add_i32 m0, s38, 0x2000
	s_add_u32 s36, s36, 0x40080
	v_lshl_add_u64 v[170:171], v[206:207], 0, s[18:19]
	s_addc_u32 s37, s37, 0
	s_add_i32 s38, s74, s3
	global_load_lds_dwordx4 v[170:171], off
	v_lshl_add_u64 v[170:171], s[36:37], 0, v[146:147]
	s_mov_b32 m0, s38
	s_nop 0
	global_load_lds_dwordx4 v[170:171], off
	v_lshl_add_u64 v[170:171], s[36:37], 0, v[150:151]
	s_add_i32 m0, s38, 0x2000
	s_nop 0
	global_load_lds_dwordx4 v[170:171], off
	v_lshl_add_u64 v[170:171], v[230:231], 0, s[18:19]
	s_mov_b32 m0, s50
	s_nop 0
	global_load_lds_dwordx4 v[170:171], off
	v_lshl_add_u64 v[170:171], v[232:233], 0, s[18:19]
	s_mov_b32 m0, s51
	s_nop 0
	global_load_lds_dwordx4 v[170:171], off
	s_waitcnt vmcnt(8)
	s_waitcnt lgkmcnt(0)
	s_barrier
	s_waitcnt lgkmcnt(0)
	v_mfma_f32_16x16x32_bf16 v[60:63], v[128:131], v[194:197], v[60:63]
	v_mfma_f32_16x16x32_bf16 v[56:59], v[136:139], v[194:197], v[56:59]
	v_mfma_f32_16x16x32_bf16 v[48:51], v[128:131], v[202:205], v[48:51]
	v_mfma_f32_16x16x32_bf16 v[44:47], v[136:139], v[202:205], v[44:47]
	v_mfma_f32_16x16x32_bf16 v[32:35], v[128:131], v[214:217], v[32:35]
	v_mfma_f32_16x16x32_bf16 v[28:31], v[136:139], v[214:217], v[28:31]
	v_mfma_f32_16x16x32_bf16 v[16:19], v[128:131], v[222:225], v[16:19]
	v_mfma_f32_16x16x32_bf16 v[12:15], v[136:139], v[222:225], v[12:15]
	v_mfma_f32_16x16x32_bf16 v[60:63], v[132:135], v[198:201], v[60:63]
	v_mfma_f32_16x16x32_bf16 v[56:59], v[140:143], v[198:201], v[56:59]
	v_mfma_f32_16x16x32_bf16 v[48:51], v[132:135], v[210:213], v[48:51]
	v_mfma_f32_16x16x32_bf16 v[44:47], v[140:143], v[210:213], v[44:47]
	v_mfma_f32_16x16x32_bf16 v[32:35], v[132:135], v[218:221], v[32:35]
	v_mfma_f32_16x16x32_bf16 v[28:31], v[140:143], v[218:221], v[28:31]
	v_mfma_f32_16x16x32_bf16 v[16:19], v[132:135], v[226:229], v[16:19]
	v_mfma_f32_16x16x32_bf16 v[12:15], v[140:143], v[226:229], v[12:15]
	v_mfma_f32_16x16x32_bf16 v[52:55], v[166:169], v[194:197], v[52:55]
	v_mfma_f32_16x16x32_bf16 v[40:43], v[186:189], v[194:197], v[40:43]
	v_mfma_f32_16x16x32_bf16 v[36:39], v[166:169], v[202:205], v[36:39]
	v_mfma_f32_16x16x32_bf16 v[24:27], v[186:189], v[202:205], v[24:27]
	v_mfma_f32_16x16x32_bf16 v[20:23], v[166:169], v[214:217], v[20:23]
	v_mfma_f32_16x16x32_bf16 v[8:11], v[186:189], v[214:217], v[8:11]
	v_mfma_f32_16x16x32_bf16 v[4:7], v[166:169], v[222:225], v[4:7]
	v_mfma_f32_16x16x32_bf16 v[0:3], v[186:189], v[222:225], v[0:3]
	v_mfma_f32_16x16x32_bf16 v[52:55], v[182:185], v[198:201], v[52:55]
	v_mfma_f32_16x16x32_bf16 v[40:43], v[190:193], v[198:201], v[40:43]
	v_mfma_f32_16x16x32_bf16 v[36:39], v[182:185], v[210:213], v[36:39]
	v_mfma_f32_16x16x32_bf16 v[24:27], v[190:193], v[210:213], v[24:27]
	v_mfma_f32_16x16x32_bf16 v[20:23], v[182:185], v[218:221], v[20:23]
	v_mfma_f32_16x16x32_bf16 v[8:11], v[190:193], v[218:221], v[8:11]
	v_mfma_f32_16x16x32_bf16 v[4:7], v[182:185], v[226:229], v[4:7]
	v_mfma_f32_16x16x32_bf16 v[0:3], v[190:193], v[226:229], v[0:3]
	s_barrier
	s_add_i32 s45, s45, 2
	s_add_u32 s0, s0, 0x100
	s_addc_u32 s1, s1, 0
	s_add_u32 s43, s43, 0x100
	s_addc_u32 s44, s44, 0
	s_cmp_gt_u32 s45, 13
	s_cbranch_scc0 .LBB0_212
	s_setprio 0
	s_and_b64 vcc, exec, s[20:21]
	s_cbranch_vccz .LBB0_215
	s_barrier

.LBB0_585:
	s_lshl_b32 s20, s49, 8
	s_ashr_i32 s21, s20, 31
	s_lshl_b64 s[20:21], s[20:21], 11
	s_add_u32 s20, s60, s20
	s_addc_u32 s21, s61, s21
	s_and_b64 s[22:23], s[6:7], exec
	s_cselect_b32 s25, s21, s27
	s_cselect_b32 s51, s20, s26
	s_ashr_i32 s19, s18, 31
	s_lshl_b64 s[22:23], s[18:19], 19
	s_add_u32 s22, s92, s22
	s_addc_u32 s23, s93, s23
	s_and_b64 s[30:31], s[6:7], exec
	s_cselect_b32 s19, s23, s29
	s_cselect_b32 s54, s22, s28
	s_add_u32 s26, s26, 0x40080
	s_addc_u32 s27, s27, 0
	s_add_u32 s55, s28, 0x100
	v_mov_b32_e32 v0, 0
	s_addc_u32 s62, s29, 0
	s_mov_b32 s63, -2
	s_waitcnt lgkmcnt(0)
	v_mov_b32_e32 v1, v0
	v_mov_b32_e32 v2, v0
	v_mov_b32_e32 v3, v0
	v_mov_b32_e32 v4, v0
	v_mov_b32_e32 v5, v0
	v_mov_b32_e32 v6, v0
	v_mov_b32_e32 v7, v0
	v_mov_b32_e32 v16, v0
	v_mov_b32_e32 v17, v0
	v_mov_b32_e32 v18, v0
	v_mov_b32_e32 v19, v0
	v_mov_b32_e32 v20, v0
	v_mov_b32_e32 v21, v0
	v_mov_b32_e32 v22, v0
	v_mov_b32_e32 v23, v0
	v_mov_b32_e32 v32, v0
	v_mov_b32_e32 v33, v0
	v_mov_b32_e32 v34, v0
	v_mov_b32_e32 v35, v0
	v_mov_b32_e32 v36, v0
	v_mov_b32_e32 v37, v0
	v_mov_b32_e32 v38, v0
	v_mov_b32_e32 v39, v0
	v_mov_b32_e32 v48, v0
	v_mov_b32_e32 v49, v0
	v_mov_b32_e32 v50, v0
	v_mov_b32_e32 v51, v0
	v_mov_b32_e32 v52, v0
	v_mov_b32_e32 v53, v0
	v_mov_b32_e32 v54, v0
	v_mov_b32_e32 v55, v0
	v_mov_b32_e32 v8, v0
	v_mov_b32_e32 v9, v0
	v_mov_b32_e32 v10, v0
	v_mov_b32_e32 v11, v0
	v_mov_b32_e32 v12, v0
	v_mov_b32_e32 v13, v0
	v_mov_b32_e32 v14, v0
	v_mov_b32_e32 v15, v0
	v_mov_b32_e32 v24, v0
	v_mov_b32_e32 v25, v0
	v_mov_b32_e32 v26, v0
	v_mov_b32_e32 v27, v0
	v_mov_b32_e32 v28, v0
	v_mov_b32_e32 v29, v0
	v_mov_b32_e32 v30, v0
	v_mov_b32_e32 v31, v0
	v_mov_b32_e32 v40, v0
	v_mov_b32_e32 v41, v0
	v_mov_b32_e32 v42, v0
	v_mov_b32_e32 v43, v0
	v_mov_b32_e32 v44, v0
	v_mov_b32_e32 v45, v0
	v_mov_b32_e32 v46, v0
	v_mov_b32_e32 v47, v0
	v_mov_b32_e32 v56, v0
	v_mov_b32_e32 v57, v0
	v_mov_b32_e32 v58, v0
	v_mov_b32_e32 v59, v0
	v_mov_b32_e32 v60, v0
	s_waitcnt lgkmcnt(0)
	v_mov_b32_e32 v61, v0
	v_mov_b32_e32 v62, v0
	v_mov_b32_e32 v63, v0
	v_mov_b32_e32 v64, v0
	v_mov_b32_e32 v65, v0
	v_mov_b32_e32 v66, v0
	v_mov_b32_e32 v67, v0
	v_mov_b32_e32 v68, v0
	v_mov_b32_e32 v69, v0
	v_mov_b32_e32 v70, v0
	v_mov_b32_e32 v71, v0
	v_mov_b32_e32 v80, v0
	v_mov_b32_e32 v81, v0
	v_mov_b32_e32 v82, v0
	v_mov_b32_e32 v83, v0
	v_mov_b32_e32 v84, v0
	v_mov_b32_e32 v85, v0
	v_mov_b32_e32 v86, v0
	v_mov_b32_e32 v87, v0
	v_mov_b32_e32 v96, v0
	v_mov_b32_e32 v97, v0
	v_mov_b32_e32 v98, v0
	v_mov_b32_e32 v99, v0
	v_mov_b32_e32 v100, v0
	v_mov_b32_e32 v101, v0
	v_mov_b32_e32 v102, v0
	v_mov_b32_e32 v103, v0
	v_mov_b32_e32 v112, v0
	v_mov_b32_e32 v113, v0
	v_mov_b32_e32 v114, v0
	v_mov_b32_e32 v115, v0
	v_mov_b32_e32 v116, v0
	v_mov_b32_e32 v117, v0
	v_mov_b32_e32 v118, v0
	v_mov_b32_e32 v119, v0
	v_mov_b32_e32 v72, v0
	v_mov_b32_e32 v73, v0
	v_mov_b32_e32 v74, v0
	v_mov_b32_e32 v75, v0
	v_mov_b32_e32 v76, v0
	v_mov_b32_e32 v77, v0
	v_mov_b32_e32 v78, v0
	v_mov_b32_e32 v79, v0
	v_mov_b32_e32 v88, v0
	v_mov_b32_e32 v89, v0
	v_mov_b32_e32 v90, v0
	v_mov_b32_e32 v91, v0
	v_mov_b32_e32 v92, v0
	v_mov_b32_e32 v93, v0
	v_mov_b32_e32 v94, v0
	v_mov_b32_e32 v95, v0
	v_mov_b32_e32 v104, v0
	v_mov_b32_e32 v105, v0
	v_mov_b32_e32 v106, v0
	v_mov_b32_e32 v107, v0
	v_mov_b32_e32 v108, v0
	v_mov_b32_e32 v109, v0
	v_mov_b32_e32 v110, v0
	v_mov_b32_e32 v111, v0
	v_mov_b32_e32 v120, v0
	v_mov_b32_e32 v121, v0
	v_mov_b32_e32 v122, v0
	v_mov_b32_e32 v123, v0
	v_mov_b32_e32 v124, v0
	v_mov_b32_e32 v125, v0
	v_mov_b32_e32 v126, v0
	v_mov_b32_e32 v127, v0
	s_setprio 0
	s_cmp_lt_u32 s3, 0x1000
	s_cbranch_scc1 .Lsprio_p5
	s_setprio 1
.Lsprio_p5:
.LBB0_586:
	ds_read_b128 v[144:147], v175
	ds_read_b128 v[148:151], v175 offset:1024
	ds_read_b128 v[152:155], v175 offset:2048
	ds_read_b128 v[156:159], v175 offset:3072
	ds_read_b128 v[160:163], v176
	ds_read_b128 v[164:167], v176 offset:1024
	ds_read_b128 v[168:171], v176 offset:2048
	ds_read_b128 v[180:183], v176 offset:3072
	s_add_u32 s28, s26, 0xfffc0080
	s_addc_u32 s29, s27, -1
	s_cmp_eq_u32 s63, 12
	s_cselect_b32 s31, s25, s29
	s_cselect_b32 s30, s51, s28
	s_cselect_b32 s29, s19, s62
	s_cselect_b32 s28, s54, s55
	v_lshl_add_u64 v[218:219], s[26:27], 0, v[136:137]
	s_add_i32 m0, s34, 0xc000
	ds_read_b128 v[184:187], v177
	ds_read_b128 v[188:191], v177 offset:1024
	ds_read_b128 v[192:195], v177 offset:2048
	ds_read_b128 v[196:199], v177 offset:3072
	ds_read_b128 v[200:203], v177 offset:4096
	ds_read_b128 v[204:207], v177 offset:5120
	ds_read_b128 v[210:213], v177 offset:6144
	ds_read_b128 v[214:217], v177 offset:7168
	global_load_lds_dwordx4 v[218:219], off
	v_lshl_add_u64 v[218:219], s[26:27], 0, v[138:139]
	s_add_i32 m0, s34, 0xe000
	s_nop 0
	global_load_lds_dwordx4 v[218:219], off
	s_waitcnt vmcnt(8)
	s_waitcnt lgkmcnt(0)
	s_barrier
	s_waitcnt lgkmcnt(0)
	v_mfma_f32_16x16x32_bf16 v[124:127], v[144:147], v[184:187], v[124:127]
	v_mfma_f32_16x16x32_bf16 v[120:123], v[152:155], v[184:187], v[120:123]
	v_mfma_f32_16x16x32_bf16 v[108:111], v[144:147], v[192:195], v[108:111]
	v_mfma_f32_16x16x32_bf16 v[104:107], v[152:155], v[192:195], v[104:107]
	v_mfma_f32_16x16x32_bf16 v[92:95], v[144:147], v[200:203], v[92:95]
	v_mfma_f32_16x16x32_bf16 v[88:91], v[152:155], v[200:203], v[88:91]
	v_mfma_f32_16x16x32_bf16 v[76:79], v[144:147], v[210:213], v[76:79]
	v_mfma_f32_16x16x32_bf16 v[72:75], v[152:155], v[210:213], v[72:75]
	v_mfma_f32_16x16x32_bf16 v[124:127], v[148:151], v[188:191], v[124:127]
	v_mfma_f32_16x16x32_bf16 v[120:123], v[156:159], v[188:191], v[120:123]
	v_mfma_f32_16x16x32_bf16 v[108:111], v[148:151], v[196:199], v[108:111]
	v_mfma_f32_16x16x32_bf16 v[104:107], v[156:159], v[196:199], v[104:107]
	v_mfma_f32_16x16x32_bf16 v[92:95], v[148:151], v[204:207], v[92:95]
	v_mfma_f32_16x16x32_bf16 v[88:91], v[156:159], v[204:207], v[88:91]
	v_mfma_f32_16x16x32_bf16 v[76:79], v[148:151], v[214:217], v[76:79]
	v_mfma_f32_16x16x32_bf16 v[72:75], v[156:159], v[214:217], v[72:75]
	v_mfma_f32_16x16x32_bf16 v[116:119], v[160:163], v[184:187], v[116:119]
	v_mfma_f32_16x16x32_bf16 v[112:115], v[168:171], v[184:187], v[112:115]
	v_mfma_f32_16x16x32_bf16 v[100:103], v[160:163], v[192:195], v[100:103]
	v_mfma_f32_16x16x32_bf16 v[96:99], v[168:171], v[192:195], v[96:99]
	v_mfma_f32_16x16x32_bf16 v[84:87], v[160:163], v[200:203], v[84:87]
	v_mfma_f32_16x16x32_bf16 v[80:83], v[168:171], v[200:203], v[80:83]
	v_mfma_f32_16x16x32_bf16 v[68:71], v[160:163], v[210:213], v[68:71]
	v_mfma_f32_16x16x32_bf16 v[64:67], v[168:171], v[210:213], v[64:67]
	v_mfma_f32_16x16x32_bf16 v[116:119], v[164:167], v[188:191], v[116:119]
	v_mfma_f32_16x16x32_bf16 v[112:115], v[180:183], v[188:191], v[112:115]
	v_mfma_f32_16x16x32_bf16 v[100:103], v[164:167], v[196:199], v[100:103]
	v_mfma_f32_16x16x32_bf16 v[96:99], v[180:183], v[196:199], v[96:99]
	v_mfma_f32_16x16x32_bf16 v[84:87], v[164:167], v[204:207], v[84:87]
	v_mfma_f32_16x16x32_bf16 v[80:83], v[180:183], v[204:207], v[80:83]
	v_mfma_f32_16x16x32_bf16 v[68:71], v[164:167], v[214:217], v[68:71]
	v_mfma_f32_16x16x32_bf16 v[64:67], v[180:183], v[214:217], v[64:67]
	s_barrier
	s_add_i32 s64, s47, s3
	v_lshl_add_u64 v[218:219], s[28:29], 0, v[130:131]
	s_mov_b32 m0, s64
	ds_read_b128 v[184:187], v177 offset:16384
	ds_read_b128 v[188:191], v177 offset:17408
	ds_read_b128 v[192:195], v177 offset:18432
	ds_read_b128 v[196:199], v177 offset:19456
	ds_read_b128 v[200:203], v177 offset:20480
	ds_read_b128 v[204:207], v177 offset:21504
	ds_read_b128 v[210:213], v177 offset:22528
	ds_read_b128 v[214:217], v177 offset:23552
	global_load_lds_dwordx4 v[218:219], off
	s_add_i32 m0, s64, 0x2000
	s_add_u32 s64, s28, 0x40000
	v_lshl_add_u64 v[220:221], s[28:29], 0, v[134:135]
	s_addc_u32 s65, s29, 0
	s_add_i32 s66, s48, s3
	global_load_lds_dwordx4 v[220:221], off
	v_lshl_add_u64 v[222:223], s[64:65], 0, v[130:131]
	s_mov_b32 m0, s66
	v_lshl_add_u64 v[224:225], s[30:31], 0, v[132:133]
	global_load_lds_dwordx4 v[222:223], off
	v_lshl_add_u64 v[222:223], s[64:65], 0, v[134:135]
	s_add_i32 m0, s66, 0x2000
	s_nop 0
	global_load_lds_dwordx4 v[222:223], off
	v_lshl_add_u64 v[222:223], s[30:31], 0, v[128:129]
	s_mov_b32 m0, s34
	s_nop 0
	global_load_lds_dwordx4 v[222:223], off
	s_mov_b32 m0, s35
	s_nop 0
	global_load_lds_dwordx4 v[224:225], off
	s_waitcnt vmcnt(8)
	s_waitcnt lgkmcnt(0)
	s_barrier
	s_waitcnt lgkmcnt(0)
	v_mfma_f32_16x16x32_bf16 v[60:63], v[144:147], v[184:187], v[60:63]
	v_mfma_f32_16x16x32_bf16 v[56:59], v[152:155], v[184:187], v[56:59]
	v_mfma_f32_16x16x32_bf16 v[44:47], v[144:147], v[192:195], v[44:47]
	v_mfma_f32_16x16x32_bf16 v[40:43], v[152:155], v[192:195], v[40:43]
	v_mfma_f32_16x16x32_bf16 v[28:31], v[144:147], v[200:203], v[28:31]
	v_mfma_f32_16x16x32_bf16 v[24:27], v[152:155], v[200:203], v[24:27]
	v_mfma_f32_16x16x32_bf16 v[12:15], v[144:147], v[210:213], v[12:15]
	v_mfma_f32_16x16x32_bf16 v[8:11], v[152:155], v[210:213], v[8:11]
	v_mfma_f32_16x16x32_bf16 v[60:63], v[148:151], v[188:191], v[60:63]
	v_mfma_f32_16x16x32_bf16 v[56:59], v[156:159], v[188:191], v[56:59]
	v_mfma_f32_16x16x32_bf16 v[44:47], v[148:151], v[196:199], v[44:47]
	v_mfma_f32_16x16x32_bf16 v[40:43], v[156:159], v[196:199], v[40:43]
	v_mfma_f32_16x16x32_bf16 v[28:31], v[148:151], v[204:207], v[28:31]
	v_mfma_f32_16x16x32_bf16 v[24:27], v[156:159], v[204:207], v[24:27]
	v_mfma_f32_16x16x32_bf16 v[12:15], v[148:151], v[214:217], v[12:15]
	v_mfma_f32_16x16x32_bf16 v[8:11], v[156:159], v[214:217], v[8:11]
	v_mfma_f32_16x16x32_bf16 v[52:55], v[160:163], v[184:187], v[52:55]
	v_mfma_f32_16x16x32_bf16 v[48:51], v[168:171], v[184:187], v[48:51]
	v_mfma_f32_16x16x32_bf16 v[36:39], v[160:163], v[192:195], v[36:39]
	v_mfma_f32_16x16x32_bf16 v[32:35], v[168:171], v[192:195], v[32:35]
	v_mfma_f32_16x16x32_bf16 v[20:23], v[160:163], v[200:203], v[20:23]
	v_mfma_f32_16x16x32_bf16 v[16:19], v[168:171], v[200:203], v[16:19]
	v_mfma_f32_16x16x32_bf16 v[4:7], v[160:163], v[210:213], v[4:7]
	v_mfma_f32_16x16x32_bf16 v[0:3], v[168:171], v[210:213], v[0:3]
	v_mfma_f32_16x16x32_bf16 v[52:55], v[164:167], v[188:191], v[52:55]
	v_mfma_f32_16x16x32_bf16 v[48:51], v[180:183], v[188:191], v[48:51]
	v_mfma_f32_16x16x32_bf16 v[36:39], v[164:167], v[196:199], v[36:39]
	v_mfma_f32_16x16x32_bf16 v[32:35], v[180:183], v[196:199], v[32:35]
	v_mfma_f32_16x16x32_bf16 v[20:23], v[164:167], v[204:207], v[20:23]
	v_mfma_f32_16x16x32_bf16 v[16:19], v[180:183], v[204:207], v[16:19]
	v_mfma_f32_16x16x32_bf16 v[4:7], v[164:167], v[214:217], v[4:7]
	v_mfma_f32_16x16x32_bf16 v[0:3], v[180:183], v[214:217], v[0:3]
	s_barrier
	s_add_i32 s64, 0, 0x18000
	s_add_i32 s65, 0, 0x1c000
	v_add_u32_e32 v156, s64, v173
	v_add_u32_e32 v179, s65, v173
	ds_read_b128 v[144:147], v156
	ds_read_b128 v[148:151], v156 offset:1024
	ds_read_b128 v[152:155], v156 offset:2048
	ds_read_b128 v[156:159], v156 offset:3072
	ds_read_b128 v[160:163], v179
	ds_read_b128 v[164:167], v179 offset:1024
	ds_read_b128 v[168:171], v179 offset:2048
	ds_read_b128 v[180:183], v179 offset:3072
	s_add_u32 s30, s30, 0x40000
	s_addc_u32 s31, s31, 0
	s_mov_b32 m0, s36
	v_lshl_add_u64 v[226:227], s[30:31], 0, v[128:129]
	ds_read_b128 v[184:187], v177 offset:32768
	ds_read_b128 v[188:191], v177 offset:33792
	ds_read_b128 v[192:195], v177 offset:34816
	ds_read_b128 v[196:199], v177 offset:35840
	ds_read_b128 v[200:203], v177 offset:36864
	ds_read_b128 v[204:207], v177 offset:37888
	ds_read_b128 v[210:213], v177 offset:38912
	ds_read_b128 v[214:217], v177 offset:39936
	global_load_lds_dwordx4 v[226:227], off
	v_lshl_add_u64 v[226:227], s[30:31], 0, v[132:133]
	s_mov_b32 m0, s37
	s_nop 0
	global_load_lds_dwordx4 v[226:227], off
	s_waitcnt vmcnt(8)
	s_waitcnt lgkmcnt(0)
	s_barrier
	s_waitcnt lgkmcnt(0)
	v_mfma_f32_16x16x32_bf16 v[124:127], v[144:147], v[184:187], v[124:127]
	v_mfma_f32_16x16x32_bf16 v[120:123], v[152:155], v[184:187], v[120:123]
	v_mfma_f32_16x16x32_bf16 v[108:111], v[144:147], v[192:195], v[108:111]
	v_mfma_f32_16x16x32_bf16 v[104:107], v[152:155], v[192:195], v[104:107]
	v_mfma_f32_16x16x32_bf16 v[92:95], v[144:147], v[200:203], v[92:95]
	v_mfma_f32_16x16x32_bf16 v[88:91], v[152:155], v[200:203], v[88:91]
	v_mfma_f32_16x16x32_bf16 v[76:79], v[144:147], v[210:213], v[76:79]
	v_mfma_f32_16x16x32_bf16 v[72:75], v[152:155], v[210:213], v[72:75]
	v_mfma_f32_16x16x32_bf16 v[124:127], v[148:151], v[188:191], v[124:127]
	v_mfma_f32_16x16x32_bf16 v[120:123], v[156:159], v[188:191], v[120:123]
	v_mfma_f32_16x16x32_bf16 v[108:111], v[148:151], v[196:199], v[108:111]
	v_mfma_f32_16x16x32_bf16 v[104:107], v[156:159], v[196:199], v[104:107]
	v_mfma_f32_16x16x32_bf16 v[92:95], v[148:151], v[204:207], v[92:95]
	v_mfma_f32_16x16x32_bf16 v[88:91], v[156:159], v[204:207], v[88:91]
	v_mfma_f32_16x16x32_bf16 v[76:79], v[148:151], v[214:217], v[76:79]
	v_mfma_f32_16x16x32_bf16 v[72:75], v[156:159], v[214:217], v[72:75]
	v_mfma_f32_16x16x32_bf16 v[116:119], v[160:163], v[184:187], v[116:119]
	v_mfma_f32_16x16x32_bf16 v[112:115], v[168:171], v[184:187], v[112:115]
	v_mfma_f32_16x16x32_bf16 v[100:103], v[160:163], v[192:195], v[100:103]
	v_mfma_f32_16x16x32_bf16 v[96:99], v[168:171], v[192:195], v[96:99]
	v_mfma_f32_16x16x32_bf16 v[84:87], v[160:163], v[200:203], v[84:87]
	v_mfma_f32_16x16x32_bf16 v[80:83], v[168:171], v[200:203], v[80:83]
	v_mfma_f32_16x16x32_bf16 v[68:71], v[160:163], v[210:213], v[68:71]
	v_mfma_f32_16x16x32_bf16 v[64:67], v[168:171], v[210:213], v[64:67]
	v_mfma_f32_16x16x32_bf16 v[116:119], v[164:167], v[188:191], v[116:119]
	v_mfma_f32_16x16x32_bf16 v[112:115], v[180:183], v[188:191], v[112:115]
	v_mfma_f32_16x16x32_bf16 v[100:103], v[164:167], v[196:199], v[100:103]
	v_mfma_f32_16x16x32_bf16 v[96:99], v[180:183], v[196:199], v[96:99]
	v_mfma_f32_16x16x32_bf16 v[84:87], v[164:167], v[204:207], v[84:87]
	v_mfma_f32_16x16x32_bf16 v[80:83], v[180:183], v[204:207], v[80:83]
	v_mfma_f32_16x16x32_bf16 v[68:71], v[164:167], v[214:217], v[68:71]
	v_mfma_f32_16x16x32_bf16 v[64:67], v[180:183], v[214:217], v[64:67]
	s_barrier
	s_add_i32 s30, s64, s3
	v_lshl_add_u64 v[218:219], v[218:219], 0, s[12:13]
	s_mov_b32 m0, s30
	ds_read_b128 v[184:187], v177 offset:49152
	ds_read_b128 v[188:191], v177 offset:50176
	ds_read_b128 v[192:195], v177 offset:51200
	ds_read_b128 v[196:199], v177 offset:52224
	ds_read_b128 v[200:203], v177 offset:53248
	ds_read_b128 v[204:207], v177 offset:54272
	ds_read_b128 v[210:213], v177 offset:55296
	ds_read_b128 v[214:217], v177 offset:56320
	global_load_lds_dwordx4 v[218:219], off
	s_add_i32 m0, s30, 0x2000
	s_add_u32 s28, s28, 0x40080
	v_lshl_add_u64 v[218:219], v[220:221], 0, s[12:13]
	s_addc_u32 s29, s29, 0
	s_add_i32 s30, s65, s3
	global_load_lds_dwordx4 v[218:219], off
	v_lshl_add_u64 v[218:219], s[28:29], 0, v[130:131]
	s_mov_b32 m0, s30
	s_nop 0
	global_load_lds_dwordx4 v[218:219], off
	v_lshl_add_u64 v[218:219], s[28:29], 0, v[134:135]
	s_add_i32 m0, s30, 0x2000
	s_nop 0
	global_load_lds_dwordx4 v[218:219], off
	v_lshl_add_u64 v[218:219], v[222:223], 0, s[12:13]
	s_mov_b32 m0, s43
	s_nop 0
	global_load_lds_dwordx4 v[218:219], off
	v_lshl_add_u64 v[218:219], v[224:225], 0, s[12:13]
	s_mov_b32 m0, s44
	s_nop 0
	global_load_lds_dwordx4 v[218:219], off
	s_waitcnt vmcnt(8)
	s_waitcnt lgkmcnt(0)
	s_barrier
	s_waitcnt lgkmcnt(0)
	v_mfma_f32_16x16x32_bf16 v[60:63], v[144:147], v[184:187], v[60:63]
	v_mfma_f32_16x16x32_bf16 v[56:59], v[152:155], v[184:187], v[56:59]
	v_mfma_f32_16x16x32_bf16 v[44:47], v[144:147], v[192:195], v[44:47]
	v_mfma_f32_16x16x32_bf16 v[40:43], v[152:155], v[192:195], v[40:43]
	v_mfma_f32_16x16x32_bf16 v[28:31], v[144:147], v[200:203], v[28:31]
	v_mfma_f32_16x16x32_bf16 v[24:27], v[152:155], v[200:203], v[24:27]
	v_mfma_f32_16x16x32_bf16 v[12:15], v[144:147], v[210:213], v[12:15]
	v_mfma_f32_16x16x32_bf16 v[8:11], v[152:155], v[210:213], v[8:11]
	v_mfma_f32_16x16x32_bf16 v[60:63], v[148:151], v[188:191], v[60:63]
	v_mfma_f32_16x16x32_bf16 v[56:59], v[156:159], v[188:191], v[56:59]
	v_mfma_f32_16x16x32_bf16 v[44:47], v[148:151], v[196:199], v[44:47]
	v_mfma_f32_16x16x32_bf16 v[40:43], v[156:159], v[196:199], v[40:43]
	v_mfma_f32_16x16x32_bf16 v[28:31], v[148:151], v[204:207], v[28:31]
	v_mfma_f32_16x16x32_bf16 v[24:27], v[156:159], v[204:207], v[24:27]
	v_mfma_f32_16x16x32_bf16 v[12:15], v[148:151], v[214:217], v[12:15]
	v_mfma_f32_16x16x32_bf16 v[8:11], v[156:159], v[214:217], v[8:11]
	v_mfma_f32_16x16x32_bf16 v[52:55], v[160:163], v[184:187], v[52:55]
	v_mfma_f32_16x16x32_bf16 v[48:51], v[168:171], v[184:187], v[48:51]
	v_mfma_f32_16x16x32_bf16 v[36:39], v[160:163], v[192:195], v[36:39]
	v_mfma_f32_16x16x32_bf16 v[32:35], v[168:171], v[192:195], v[32:35]
	v_mfma_f32_16x16x32_bf16 v[20:23], v[160:163], v[200:203], v[20:23]
	v_mfma_f32_16x16x32_bf16 v[16:19], v[168:171], v[200:203], v[16:19]
	v_mfma_f32_16x16x32_bf16 v[4:7], v[160:163], v[210:213], v[4:7]
	v_mfma_f32_16x16x32_bf16 v[0:3], v[168:171], v[210:213], v[0:3]
	v_mfma_f32_16x16x32_bf16 v[52:55], v[164:167], v[188:191], v[52:55]
	v_mfma_f32_16x16x32_bf16 v[48:51], v[180:183], v[188:191], v[48:51]
	v_mfma_f32_16x16x32_bf16 v[36:39], v[164:167], v[196:199], v[36:39]
	v_mfma_f32_16x16x32_bf16 v[32:35], v[180:183], v[196:199], v[32:35]
	v_mfma_f32_16x16x32_bf16 v[20:23], v[164:167], v[204:207], v[20:23]
	v_mfma_f32_16x16x32_bf16 v[16:19], v[180:183], v[204:207], v[16:19]
	v_mfma_f32_16x16x32_bf16 v[4:7], v[164:167], v[214:217], v[4:7]
	v_mfma_f32_16x16x32_bf16 v[0:3], v[180:183], v[214:217], v[0:3]
	s_barrier
	s_add_i32 s63, s63, 2
	s_add_u32 s26, s26, 0x100
	s_addc_u32 s27, s27, 0
	s_add_u32 s55, s55, 0x100
	s_addc_u32 s62, s62, 0
	s_cmp_gt_u32 s63, 13
	s_cbranch_scc0 .LBB0_586
	s_setprio 0
	s_and_b64 vcc, exec, s[16:17]
	s_cbranch_vccz .LBB0_589
	s_barrier

.LBB0_684:
	s_ashr_i32 s41, s40, 31
	s_lshl_b64 s[22:23], s[40:41], 19
	s_add_u32 s44, s56, s22
	s_addc_u32 s45, s57, s23
	s_and_b64 s[0:1], s[0:1], exec
	s_cselect_b32 s13, s45, s17
	s_cselect_b32 s21, s44, s16
	s_add_u32 s0, s18, 0x40080
	s_addc_u32 s1, s19, 0
	s_add_u32 s22, s16, 0x100
	v_mov_b32_e32 v36, 0
	s_addc_u32 s23, s17, 0
	s_mov_b32 s24, -2
	v_mov_b32_e32 v37, v36
	v_mov_b32_e32 v38, v36
	v_mov_b32_e32 v39, v36
	v_mov_b32_e32 v104, v36
	v_mov_b32_e32 v105, v36
	v_mov_b32_e32 v106, v36
	v_mov_b32_e32 v107, v36
	v_mov_b32_e32 v0, v36
	v_mov_b32_e32 v1, v36
	v_mov_b32_e32 v2, v36
	v_mov_b32_e32 v3, v36
	s_waitcnt vmcnt(0)
	v_mov_b32_e32 v72, v36
	v_mov_b32_e32 v73, v36
	v_mov_b32_e32 v74, v36
	v_mov_b32_e32 v75, v36
	v_mov_b32_e32 v8, v36
	v_mov_b32_e32 v9, v36
	v_mov_b32_e32 v10, v36
	v_mov_b32_e32 v11, v36
	v_mov_b32_e32 v80, v36
	v_mov_b32_e32 v81, v36
	v_mov_b32_e32 v82, v36
	v_mov_b32_e32 v83, v36
	v_mov_b32_e32 v16, v36
	v_mov_b32_e32 v17, v36
	v_mov_b32_e32 v18, v36
	v_mov_b32_e32 v19, v36
	v_mov_b32_e32 v88, v36
	v_mov_b32_e32 v89, v36
	v_mov_b32_e32 v90, v36
	v_mov_b32_e32 v91, v36
	v_mov_b32_e32 v24, v36
	v_mov_b32_e32 v25, v36
	v_mov_b32_e32 v26, v36
	v_mov_b32_e32 v27, v36
	v_mov_b32_e32 v96, v36
	v_mov_b32_e32 v97, v36
	v_mov_b32_e32 v98, v36
	v_mov_b32_e32 v99, v36
	v_mov_b32_e32 v4, v36
	v_mov_b32_e32 v5, v36
	v_mov_b32_e32 v6, v36
	v_mov_b32_e32 v7, v36
	v_mov_b32_e32 v76, v36
	v_mov_b32_e32 v77, v36
	v_mov_b32_e32 v78, v36
	v_mov_b32_e32 v79, v36
	v_mov_b32_e32 v12, v36
	v_mov_b32_e32 v13, v36
	v_mov_b32_e32 v14, v36
	v_mov_b32_e32 v15, v36
	v_mov_b32_e32 v84, v36
	v_mov_b32_e32 v85, v36
	v_mov_b32_e32 v86, v36
	v_mov_b32_e32 v87, v36
	v_mov_b32_e32 v20, v36
	v_mov_b32_e32 v21, v36
	v_mov_b32_e32 v22, v36
	v_mov_b32_e32 v23, v36
	v_mov_b32_e32 v92, v36
	v_mov_b32_e32 v93, v36
	v_mov_b32_e32 v94, v36
	v_mov_b32_e32 v95, v36
	v_mov_b32_e32 v68, v36
	v_mov_b32_e32 v69, v36
	v_mov_b32_e32 v70, v36
	v_mov_b32_e32 v71, v36
	v_mov_b32_e32 v112, v36
	v_mov_b32_e32 v113, v36
	v_mov_b32_e32 v114, v36
	v_mov_b32_e32 v115, v36
	v_mov_b32_e32 v28, v36
	v_mov_b32_e32 v29, v36
	v_mov_b32_e32 v30, v36
	v_mov_b32_e32 v31, v36
	v_mov_b32_e32 v100, v36
	v_mov_b32_e32 v101, v36
	v_mov_b32_e32 v102, v36
	v_mov_b32_e32 v103, v36
	v_mov_b32_e32 v48, v36
	v_mov_b32_e32 v49, v36
	v_mov_b32_e32 v50, v36
	v_mov_b32_e32 v51, v36
	v_mov_b32_e32 v144, v36
	v_mov_b32_e32 v145, v36
	v_mov_b32_e32 v146, v36
	v_mov_b32_e32 v147, v36
	v_mov_b32_e32 v56, v36
	v_mov_b32_e32 v57, v36
	v_mov_b32_e32 v58, v36
	v_mov_b32_e32 v59, v36
	v_mov_b32_e32 v152, v36
	v_mov_b32_e32 v153, v36
	v_mov_b32_e32 v154, v36
	v_mov_b32_e32 v155, v36
	v_mov_b32_e32 v64, v36
	v_mov_b32_e32 v65, v36
	v_mov_b32_e32 v66, v36
	v_mov_b32_e32 v67, v36
	v_mov_b32_e32 v116, v36
	v_mov_b32_e32 v117, v36
	v_mov_b32_e32 v118, v36
	v_mov_b32_e32 v119, v36
	v_mov_b32_e32 v32, v36
	v_mov_b32_e32 v33, v36
	v_mov_b32_e32 v34, v36
	v_mov_b32_e32 v35, v36
	v_mov_b32_e32 v108, v36
	v_mov_b32_e32 v109, v36
	v_mov_b32_e32 v110, v36
	v_mov_b32_e32 v111, v36
	v_mov_b32_e32 v52, v36
	v_mov_b32_e32 v53, v36
	v_mov_b32_e32 v54, v36
	v_mov_b32_e32 v55, v36
	v_mov_b32_e32 v148, v36
	v_mov_b32_e32 v149, v36
	v_mov_b32_e32 v150, v36
	v_mov_b32_e32 v151, v36
	v_mov_b32_e32 v60, v36
	v_mov_b32_e32 v61, v36
	v_mov_b32_e32 v62, v36
	v_mov_b32_e32 v63, v36
	v_mov_b32_e32 v156, v36
	v_mov_b32_e32 v157, v36
	v_mov_b32_e32 v158, v36
	v_mov_b32_e32 v159, v36
	s_setprio 0
	s_cmp_lt_u32 s3, 0x1000
	s_cbranch_scc1 .Lsprio_p7
	s_setprio 1
.Lsprio_p7:
.LBB0_685:
	ds_read_b128 v[40:43], v212
	ds_read_b128 v[44:47], v212 offset:1024
	ds_read_b128 v[120:123], v212 offset:2048
	ds_read_b128 v[124:127], v212 offset:3072
	ds_read_b128 v[128:131], v213
	ds_read_b128 v[132:135], v213 offset:1024
	ds_read_b128 v[136:139], v213 offset:2048
	ds_read_b128 v[140:143], v213 offset:3072
	s_add_u32 s16, s0, 0xfffc0080
	s_addc_u32 s17, s1, -1
	s_cmp_eq_u32 s24, 12
	s_cselect_b32 s19, s43, s17
	s_cselect_b32 s18, s42, s16
	s_cselect_b32 s17, s13, s23
	s_cselect_b32 s16, s21, s22
	v_lshl_add_u64 v[226:227], s[0:1], 0, v[184:185]
	s_add_i32 m0, s48, 0xc000
	ds_read_b128 v[160:163], v214
	ds_read_b128 v[164:167], v214 offset:1024
	ds_read_b128 v[168:171], v214 offset:2048
	ds_read_b128 v[172:175], v214 offset:3072
	ds_read_b128 v[192:195], v214 offset:4096
	ds_read_b128 v[196:199], v214 offset:5120
	ds_read_b128 v[218:221], v214 offset:6144
	ds_read_b128 v[222:225], v214 offset:7168
	global_load_lds_dwordx4 v[226:227], off
	v_lshl_add_u64 v[226:227], s[0:1], 0, v[186:187]
	s_add_i32 m0, s48, 0xe000
	s_nop 0
	global_load_lds_dwordx4 v[226:227], off
	s_waitcnt vmcnt(8)
	s_waitcnt lgkmcnt(0)
	s_barrier
	s_waitcnt lgkmcnt(0)
	v_mfma_f32_16x16x32_bf16 v[156:159], v[40:43], v[160:163], v[156:159]
	v_mfma_f32_16x16x32_bf16 v[60:63], v[120:123], v[160:163], v[60:63]
	v_mfma_f32_16x16x32_bf16 v[148:151], v[40:43], v[168:171], v[148:151]
	v_mfma_f32_16x16x32_bf16 v[52:55], v[120:123], v[168:171], v[52:55]
	v_mfma_f32_16x16x32_bf16 v[108:111], v[40:43], v[192:195], v[108:111]
	v_mfma_f32_16x16x32_bf16 v[32:35], v[120:123], v[192:195], v[32:35]
	v_mfma_f32_16x16x32_bf16 v[116:119], v[40:43], v[218:221], v[116:119]
	v_mfma_f32_16x16x32_bf16 v[64:67], v[120:123], v[218:221], v[64:67]
	v_mfma_f32_16x16x32_bf16 v[156:159], v[44:47], v[164:167], v[156:159]
	v_mfma_f32_16x16x32_bf16 v[60:63], v[124:127], v[164:167], v[60:63]
	v_mfma_f32_16x16x32_bf16 v[148:151], v[44:47], v[172:175], v[148:151]
	v_mfma_f32_16x16x32_bf16 v[52:55], v[124:127], v[172:175], v[52:55]
	v_mfma_f32_16x16x32_bf16 v[108:111], v[44:47], v[196:199], v[108:111]
	v_mfma_f32_16x16x32_bf16 v[32:35], v[124:127], v[196:199], v[32:35]
	v_mfma_f32_16x16x32_bf16 v[116:119], v[44:47], v[222:225], v[116:119]
	v_mfma_f32_16x16x32_bf16 v[64:67], v[124:127], v[222:225], v[64:67]
	v_mfma_f32_16x16x32_bf16 v[152:155], v[128:131], v[160:163], v[152:155]
	v_mfma_f32_16x16x32_bf16 v[56:59], v[136:139], v[160:163], v[56:59]
	v_mfma_f32_16x16x32_bf16 v[144:147], v[128:131], v[168:171], v[144:147]
	v_mfma_f32_16x16x32_bf16 v[48:51], v[136:139], v[168:171], v[48:51]
	v_mfma_f32_16x16x32_bf16 v[100:103], v[128:131], v[192:195], v[100:103]
	v_mfma_f32_16x16x32_bf16 v[28:31], v[136:139], v[192:195], v[28:31]
	v_mfma_f32_16x16x32_bf16 v[112:115], v[128:131], v[218:221], v[112:115]
	v_mfma_f32_16x16x32_bf16 v[68:71], v[136:139], v[218:221], v[68:71]
	v_mfma_f32_16x16x32_bf16 v[152:155], v[132:135], v[164:167], v[152:155]
	v_mfma_f32_16x16x32_bf16 v[56:59], v[140:143], v[164:167], v[56:59]
	v_mfma_f32_16x16x32_bf16 v[144:147], v[132:135], v[172:175], v[144:147]
	v_mfma_f32_16x16x32_bf16 v[48:51], v[140:143], v[172:175], v[48:51]
	v_mfma_f32_16x16x32_bf16 v[100:103], v[132:135], v[196:199], v[100:103]
	v_mfma_f32_16x16x32_bf16 v[28:31], v[140:143], v[196:199], v[28:31]
	v_mfma_f32_16x16x32_bf16 v[112:115], v[132:135], v[222:225], v[112:115]
	v_mfma_f32_16x16x32_bf16 v[68:71], v[140:143], v[222:225], v[68:71]
	s_barrier
	s_add_i32 s25, s65, s3
	v_lshl_add_u64 v[226:227], s[16:17], 0, v[178:179]
	s_mov_b32 m0, s25
	ds_read_b128 v[160:163], v214 offset:16384
	ds_read_b128 v[164:167], v214 offset:17408
	ds_read_b128 v[168:171], v214 offset:18432
	ds_read_b128 v[172:175], v214 offset:19456
	ds_read_b128 v[192:195], v214 offset:20480
	ds_read_b128 v[196:199], v214 offset:21504
	ds_read_b128 v[218:221], v214 offset:22528
	ds_read_b128 v[222:225], v214 offset:23552
	global_load_lds_dwordx4 v[226:227], off
	s_add_i32 m0, s25, 0x2000
	s_add_u32 s26, s16, 0x40000
	v_lshl_add_u64 v[228:229], s[16:17], 0, v[182:183]
	s_addc_u32 s27, s17, 0
	s_add_i32 s25, s66, s3
	global_load_lds_dwordx4 v[228:229], off
	v_lshl_add_u64 v[230:231], s[26:27], 0, v[178:179]
	s_mov_b32 m0, s25
	v_lshl_add_u64 v[232:233], s[18:19], 0, v[180:181]
	global_load_lds_dwordx4 v[230:231], off
	v_lshl_add_u64 v[230:231], s[26:27], 0, v[182:183]
	s_add_i32 m0, s25, 0x2000
	s_nop 0
	global_load_lds_dwordx4 v[230:231], off
	v_lshl_add_u64 v[230:231], s[18:19], 0, v[176:177]
	s_mov_b32 m0, s48
	s_nop 0
	global_load_lds_dwordx4 v[230:231], off
	s_mov_b32 m0, s49
	s_nop 0
	global_load_lds_dwordx4 v[232:233], off
	s_waitcnt vmcnt(8)
	s_waitcnt lgkmcnt(0)
	s_barrier
	s_waitcnt lgkmcnt(0)
	v_mfma_f32_16x16x32_bf16 v[92:95], v[40:43], v[160:163], v[92:95]
	v_mfma_f32_16x16x32_bf16 v[20:23], v[120:123], v[160:163], v[20:23]
	v_mfma_f32_16x16x32_bf16 v[84:87], v[40:43], v[168:171], v[84:87]
	v_mfma_f32_16x16x32_bf16 v[12:15], v[120:123], v[168:171], v[12:15]
	v_mfma_f32_16x16x32_bf16 v[76:79], v[40:43], v[192:195], v[76:79]
	v_mfma_f32_16x16x32_bf16 v[4:7], v[120:123], v[192:195], v[4:7]
	v_mfma_f32_16x16x32_bf16 v[24:27], v[120:123], v[218:221], v[24:27]
	v_mfma_f32_16x16x32_bf16 v[92:95], v[44:47], v[164:167], v[92:95]
	v_mfma_f32_16x16x32_bf16 v[20:23], v[124:127], v[164:167], v[20:23]
	v_mfma_f32_16x16x32_bf16 v[84:87], v[44:47], v[172:175], v[84:87]
	v_mfma_f32_16x16x32_bf16 v[12:15], v[124:127], v[172:175], v[12:15]
	v_mfma_f32_16x16x32_bf16 v[76:79], v[44:47], v[196:199], v[76:79]
	v_mfma_f32_16x16x32_bf16 v[4:7], v[124:127], v[196:199], v[4:7]
	v_mfma_f32_16x16x32_bf16 v[40:43], v[40:43], v[218:221], v[96:99]
	v_mfma_f32_16x16x32_bf16 v[24:27], v[124:127], v[222:225], v[24:27]
	v_mfma_f32_16x16x32_bf16 v[40:43], v[44:47], v[222:225], v[40:43]
	v_mfma_f32_16x16x32_bf16 v[44:47], v[128:131], v[160:163], v[88:91]
	v_mfma_f32_16x16x32_bf16 v[16:19], v[136:139], v[160:163], v[16:19]
	v_mfma_f32_16x16x32_bf16 v[80:83], v[128:131], v[168:171], v[80:83]
	v_mfma_f32_16x16x32_bf16 v[8:11], v[136:139], v[168:171], v[8:11]
	v_mfma_f32_16x16x32_bf16 v[72:75], v[128:131], v[192:195], v[72:75]
	v_mfma_f32_16x16x32_bf16 v[0:3], v[136:139], v[192:195], v[0:3]
	v_mfma_f32_16x16x32_bf16 v[88:91], v[128:131], v[218:221], v[104:107]
	v_mfma_f32_16x16x32_bf16 v[36:39], v[136:139], v[218:221], v[36:39]
	v_mfma_f32_16x16x32_bf16 v[16:19], v[140:143], v[164:167], v[16:19]
	v_mfma_f32_16x16x32_bf16 v[80:83], v[132:135], v[172:175], v[80:83]
	v_mfma_f32_16x16x32_bf16 v[8:11], v[140:143], v[172:175], v[8:11]
	v_mfma_f32_16x16x32_bf16 v[72:75], v[132:135], v[196:199], v[72:75]
	v_mfma_f32_16x16x32_bf16 v[0:3], v[140:143], v[196:199], v[0:3]
	v_mfma_f32_16x16x32_bf16 v[104:107], v[132:135], v[222:225], v[88:91]
	v_mfma_f32_16x16x32_bf16 v[36:39], v[140:143], v[222:225], v[36:39]
	v_mfma_f32_16x16x32_bf16 v[44:47], v[132:135], v[164:167], v[44:47]
	s_barrier
	s_add_i32 s25, 0, 0x18000
	s_add_i32 s26, 0, 0x1c000
	v_add_u32_e32 v124, s25, v201
	v_add_u32_e32 v140, s26, v201
	ds_read_b128 v[88:91], v124
	ds_read_b128 v[96:99], v124 offset:1024
	ds_read_b128 v[120:123], v124 offset:2048
	ds_read_b128 v[124:127], v124 offset:3072
	ds_read_b128 v[128:131], v140
	ds_read_b128 v[132:135], v140 offset:1024
	ds_read_b128 v[136:139], v140 offset:2048
	ds_read_b128 v[140:143], v140 offset:3072
	s_add_u32 s18, s18, 0x40000
	s_addc_u32 s19, s19, 0
	s_mov_b32 m0, s50
	v_lshl_add_u64 v[234:235], s[18:19], 0, v[176:177]
	ds_read_b128 v[160:163], v214 offset:32768
	ds_read_b128 v[164:167], v214 offset:33792
	ds_read_b128 v[168:171], v214 offset:34816
	ds_read_b128 v[172:175], v214 offset:35840
	ds_read_b128 v[192:195], v214 offset:36864
	ds_read_b128 v[196:199], v214 offset:37888
	ds_read_b128 v[218:221], v214 offset:38912
	ds_read_b128 v[222:225], v214 offset:39936
	global_load_lds_dwordx4 v[234:235], off
	v_lshl_add_u64 v[234:235], s[18:19], 0, v[180:181]
	s_mov_b32 m0, s51
	s_nop 0
	global_load_lds_dwordx4 v[234:235], off
	s_waitcnt vmcnt(8)
	s_waitcnt lgkmcnt(0)
	s_barrier
	s_waitcnt lgkmcnt(0)
	v_mfma_f32_16x16x32_bf16 v[156:159], v[88:91], v[160:163], v[156:159]
	v_mfma_f32_16x16x32_bf16 v[60:63], v[120:123], v[160:163], v[60:63]
	v_mfma_f32_16x16x32_bf16 v[148:151], v[88:91], v[168:171], v[148:151]
	v_mfma_f32_16x16x32_bf16 v[52:55], v[120:123], v[168:171], v[52:55]
	v_mfma_f32_16x16x32_bf16 v[108:111], v[88:91], v[192:195], v[108:111]
	v_mfma_f32_16x16x32_bf16 v[32:35], v[120:123], v[192:195], v[32:35]
	v_mfma_f32_16x16x32_bf16 v[116:119], v[88:91], v[218:221], v[116:119]
	v_mfma_f32_16x16x32_bf16 v[64:67], v[120:123], v[218:221], v[64:67]
	v_mfma_f32_16x16x32_bf16 v[156:159], v[96:99], v[164:167], v[156:159]
	v_mfma_f32_16x16x32_bf16 v[60:63], v[124:127], v[164:167], v[60:63]
	v_mfma_f32_16x16x32_bf16 v[148:151], v[96:99], v[172:175], v[148:151]
	v_mfma_f32_16x16x32_bf16 v[52:55], v[124:127], v[172:175], v[52:55]
	v_mfma_f32_16x16x32_bf16 v[108:111], v[96:99], v[196:199], v[108:111]
	v_mfma_f32_16x16x32_bf16 v[32:35], v[124:127], v[196:199], v[32:35]
	v_mfma_f32_16x16x32_bf16 v[116:119], v[96:99], v[222:225], v[116:119]
	v_mfma_f32_16x16x32_bf16 v[64:67], v[124:127], v[222:225], v[64:67]
	v_mfma_f32_16x16x32_bf16 v[152:155], v[128:131], v[160:163], v[152:155]
	v_mfma_f32_16x16x32_bf16 v[56:59], v[136:139], v[160:163], v[56:59]
	v_mfma_f32_16x16x32_bf16 v[144:147], v[128:131], v[168:171], v[144:147]
	v_mfma_f32_16x16x32_bf16 v[48:51], v[136:139], v[168:171], v[48:51]
	v_mfma_f32_16x16x32_bf16 v[100:103], v[128:131], v[192:195], v[100:103]
	v_mfma_f32_16x16x32_bf16 v[28:31], v[136:139], v[192:195], v[28:31]
	v_mfma_f32_16x16x32_bf16 v[112:115], v[128:131], v[218:221], v[112:115]
	v_mfma_f32_16x16x32_bf16 v[68:71], v[136:139], v[218:221], v[68:71]
	v_mfma_f32_16x16x32_bf16 v[152:155], v[132:135], v[164:167], v[152:155]
	v_mfma_f32_16x16x32_bf16 v[56:59], v[140:143], v[164:167], v[56:59]
	v_mfma_f32_16x16x32_bf16 v[144:147], v[132:135], v[172:175], v[144:147]
	v_mfma_f32_16x16x32_bf16 v[48:51], v[140:143], v[172:175], v[48:51]
	v_mfma_f32_16x16x32_bf16 v[100:103], v[132:135], v[196:199], v[100:103]
	v_mfma_f32_16x16x32_bf16 v[28:31], v[140:143], v[196:199], v[28:31]
	v_mfma_f32_16x16x32_bf16 v[112:115], v[132:135], v[222:225], v[112:115]
	v_mfma_f32_16x16x32_bf16 v[68:71], v[140:143], v[222:225], v[68:71]
	s_barrier
	s_add_i32 s18, s25, s3
	v_lshl_add_u64 v[226:227], v[226:227], 0, s[36:37]
	s_mov_b32 m0, s18
	ds_read_b128 v[160:163], v214 offset:49152
	ds_read_b128 v[164:167], v214 offset:50176
	ds_read_b128 v[168:171], v214 offset:51200
	ds_read_b128 v[172:175], v214 offset:52224
	ds_read_b128 v[192:195], v214 offset:53248
	ds_read_b128 v[196:199], v214 offset:54272
	ds_read_b128 v[218:221], v214 offset:55296
	ds_read_b128 v[222:225], v214 offset:56320
	s_cmp_lg_u32 s24, 12
	s_cbranch_scc1 .Lp7_nopf
	s_mul_hi_i32 s46, s20, 0x3e0f83e1
	s_lshr_b32 s47, s46, 31
	s_ashr_i32 s46, s46, 3
	s_add_i32 s46, s46, s47
	s_mul_i32 s47, s46, 33
	s_sub_i32 s47, s20, s47
	s_mul_i32 s47, s47, 0xfe
	s_min_i32 s47, s47, 0x1f00
	s_lshl_b32 s41, s46, 13
	s_add_i32 s41, s41, s47
	s_mulk_i32 s46, 0x1600
	s_lshl_b32 s46, s46, 2
	s_add_u32 s46, s53, s46
	s_addc_u32 s47, s54, 0
	v_lshl_or_b32 v209, s12, 8, v211
	v_lshlrev_b32_e32 v209, 2, v209
	v_add_u32_e32 v210, s41, v200
	v_lshlrev_b32_e32 v210, 2, v210
	global_load_dwordx4 v[236:239], v209, s[46:47] offset:16
	global_load_dwordx4 v[240:243], v209, s[46:47]
	global_load_dwordx4 v[246:249], v209, s[46:47] offset:528
	global_load_dwordx4 v[250:253], v209, s[46:47] offset:512
	global_load_dword v244, v210, s[96:97] offset:192
	global_load_dword v245, v210, s[96:97] offset:704
	global_load_dword v208, v210, s[96:97]
	global_load_dword v203, v210, s[96:97] offset:64
	global_load_dword v204, v210, s[96:97] offset:128
	global_load_dword v205, v210, s[96:97] offset:512
	global_load_dword v206, v210, s[96:97] offset:576
	global_load_dword v207, v210, s[96:97] offset:640

.Lp7_wdone:
	s_waitcnt lgkmcnt(0)
	s_barrier
	s_waitcnt lgkmcnt(0)
	v_mfma_f32_16x16x32_bf16 v[92:95], v[88:91], v[160:163], v[92:95]
	v_mfma_f32_16x16x32_bf16 v[20:23], v[120:123], v[160:163], v[20:23]
	v_mfma_f32_16x16x32_bf16 v[84:87], v[88:91], v[168:171], v[84:87]
	v_mfma_f32_16x16x32_bf16 v[12:15], v[120:123], v[168:171], v[12:15]
	v_mfma_f32_16x16x32_bf16 v[76:79], v[88:91], v[192:195], v[76:79]
	v_mfma_f32_16x16x32_bf16 v[4:7], v[120:123], v[192:195], v[4:7]
	v_mfma_f32_16x16x32_bf16 v[40:43], v[88:91], v[218:221], v[40:43]
	v_mfma_f32_16x16x32_bf16 v[24:27], v[120:123], v[218:221], v[24:27]
	v_mfma_f32_16x16x32_bf16 v[92:95], v[96:99], v[164:167], v[92:95]
	v_mfma_f32_16x16x32_bf16 v[20:23], v[124:127], v[164:167], v[20:23]
	v_mfma_f32_16x16x32_bf16 v[84:87], v[96:99], v[172:175], v[84:87]
	v_mfma_f32_16x16x32_bf16 v[12:15], v[124:127], v[172:175], v[12:15]
	v_mfma_f32_16x16x32_bf16 v[76:79], v[96:99], v[196:199], v[76:79]
	v_mfma_f32_16x16x32_bf16 v[4:7], v[124:127], v[196:199], v[4:7]
	v_mfma_f32_16x16x32_bf16 v[96:99], v[96:99], v[222:225], v[40:43]
	v_mfma_f32_16x16x32_bf16 v[24:27], v[124:127], v[222:225], v[24:27]
	v_mfma_f32_16x16x32_bf16 v[40:43], v[128:131], v[160:163], v[44:47]
	v_mfma_f32_16x16x32_bf16 v[88:91], v[132:135], v[164:167], v[40:43]
	v_mfma_f32_16x16x32_bf16 v[40:43], v[128:131], v[168:171], v[80:83]
	v_mfma_f32_16x16x32_bf16 v[80:83], v[132:135], v[172:175], v[40:43]
	v_mfma_f32_16x16x32_bf16 v[40:43], v[128:131], v[192:195], v[72:75]
	v_mfma_f32_16x16x32_bf16 v[16:19], v[136:139], v[160:163], v[16:19]
	v_mfma_f32_16x16x32_bf16 v[8:11], v[136:139], v[168:171], v[8:11]
	v_mfma_f32_16x16x32_bf16 v[72:75], v[132:135], v[196:199], v[40:43]
	v_mfma_f32_16x16x32_bf16 v[0:3], v[136:139], v[192:195], v[0:3]
	v_mfma_f32_16x16x32_bf16 v[40:43], v[128:131], v[218:221], v[104:107]
	v_mfma_f32_16x16x32_bf16 v[36:39], v[136:139], v[218:221], v[36:39]
	v_mfma_f32_16x16x32_bf16 v[16:19], v[140:143], v[164:167], v[16:19]
	v_mfma_f32_16x16x32_bf16 v[8:11], v[140:143], v[172:175], v[8:11]
	v_mfma_f32_16x16x32_bf16 v[0:3], v[140:143], v[196:199], v[0:3]
	v_mfma_f32_16x16x32_bf16 v[104:107], v[132:135], v[222:225], v[40:43]
	v_mfma_f32_16x16x32_bf16 v[36:39], v[140:143], v[222:225], v[36:39]
	s_barrier
	s_add_i32 s24, s24, 2
	s_add_u32 s0, s0, 0x100
	s_addc_u32 s1, s1, 0
	s_add_u32 s22, s22, 0x100
	s_addc_u32 s23, s23, 0
	s_cmp_gt_u32 s24, 13
	s_cbranch_scc0 .LBB0_685
	s_setprio 0
	s_and_b64 vcc, exec, s[38:39]
	s_cbranch_vccz .LBB0_688
	s_barrier
